# grid barrier: non-leader workgroups poll the top-level generation word directly; XCD leader skips the per-XCD generation bump
# baseline (speedup 1.0000x reference)
.LBB0_219:
	s_or_b64 exec, exec, s[6:7]
	v_cvt_f32_u32_e32 v5, v3
	s_waitcnt vmcnt(0)
	v_readfirstlane_b32 s6, v4
	v_sub_u32_e32 v4, 0, v3
	v_rcp_iflag_f32_e32 v5, v5
	v_add_u32_e32 v6, s6, v0
	v_mul_f32_e32 v5, 0x4f7ffffe, v5
	v_cvt_u32_f32_e32 v5, v5
	v_mul_lo_u32 v0, v4, v5
	v_mul_hi_u32 v0, v5, v0
	v_add_u32_e32 v0, v5, v0
	v_mul_hi_u32 v0, v6, v0
	v_mul_lo_u32 v4, v0, v3
	v_sub_u32_e32 v4, v6, v4
	v_add_u32_e32 v5, 1, v0
	v_cmp_ge_u32_e32 vcc, v4, v3
	s_nop 1
	v_cndmask_b32_e32 v0, v0, v5, vcc
	v_sub_u32_e32 v5, v4, v3
	v_cndmask_b32_e32 v4, v4, v5, vcc
	v_add_u32_e32 v5, 1, v0
	v_cmp_ge_u32_e32 vcc, v4, v3
	v_add_u32_e32 v4, 1, v6
	s_nop 0
	v_cndmask_b32_e32 v0, v0, v5, vcc
	v_mul_lo_u32 v5, v3, v0
	v_add_u32_e32 v3, v5, v3
	v_cmp_ne_u32_e32 vcc, v4, v3
	s_and_saveexec_b64 s[6:7], vcc
	s_xor_b64 s[6:7], exec, s[6:7]
	s_cbranch_execz .LBB0_233
	s_waitcnt lgkmcnt(0)
	global_load_dword v2, v1, s[60:61] sc1
	s_waitcnt vmcnt(0)
	v_cmp_eq_u32_e32 vcc, v2, v0
	s_and_saveexec_b64 s[8:9], vcc
	s_cbranch_execz .LBB0_232
	s_mov_b32 s15, 1
	s_mov_b64 s[10:11], 0
	s_branch .LBB0_223

.LBB0_250:
	s_or_b64 exec, exec, s[6:7]
	s_mov_b64 s[6:7], exec
	v_mbcnt_lo_u32_b32 v0, s6, 0
	v_mbcnt_hi_u32_b32 v0, s7, v0
	v_cmp_eq_u32_e32 vcc, 0, v0
	s_waitcnt vmcnt(0)
	buffer_inv sc1
	s_and_saveexec_b64 s[8:9], vcc
	s_cbranch_execz .LBB0_252
	s_bcnt1_i32_b64 s6, s[6:7]
	v_mov_b32_e32 v0, s6
	s_nop 0

.LBB0_310:
	s_or_b64 exec, exec, s[8:9]
	v_cvt_f32_u32_e32 v5, v3
	s_waitcnt vmcnt(0)
	v_readfirstlane_b32 s8, v4
	v_sub_u32_e32 v4, 0, v3
	v_rcp_iflag_f32_e32 v5, v5
	v_add_u32_e32 v6, s8, v0
	v_mul_f32_e32 v5, 0x4f7ffffe, v5
	v_cvt_u32_f32_e32 v5, v5
	v_mul_lo_u32 v0, v4, v5
	v_mul_hi_u32 v0, v5, v0
	v_add_u32_e32 v0, v5, v0
	v_mul_hi_u32 v0, v6, v0
	v_mul_lo_u32 v4, v0, v3
	v_sub_u32_e32 v4, v6, v4
	v_add_u32_e32 v5, 1, v0
	v_cmp_ge_u32_e32 vcc, v4, v3
	s_nop 1
	v_cndmask_b32_e32 v0, v0, v5, vcc
	v_sub_u32_e32 v5, v4, v3
	v_cndmask_b32_e32 v4, v4, v5, vcc
	v_add_u32_e32 v5, 1, v0
	v_cmp_ge_u32_e32 vcc, v4, v3
	v_add_u32_e32 v4, 1, v6
	s_nop 0
	v_cndmask_b32_e32 v0, v0, v5, vcc
	v_mul_lo_u32 v5, v3, v0
	v_add_u32_e32 v3, v5, v3
	v_cmp_ne_u32_e32 vcc, v4, v3
	s_and_saveexec_b64 s[8:9], vcc
	s_xor_b64 s[8:9], exec, s[8:9]
	s_cbranch_execz .LBB0_324
	s_waitcnt lgkmcnt(0)
	global_load_dword v2, v1, s[60:61] sc1
	s_waitcnt vmcnt(0)
	v_cmp_eq_u32_e32 vcc, v2, v0
	s_and_saveexec_b64 s[10:11], vcc
	s_cbranch_execz .LBB0_323
	s_mov_b32 s15, 1
	s_mov_b64 s[12:13], 0
	s_branch .LBB0_314

.LBB0_341:
	s_or_b64 exec, exec, s[8:9]
	s_mov_b64 s[8:9], exec
	v_mbcnt_lo_u32_b32 v0, s8, 0
	v_mbcnt_hi_u32_b32 v0, s9, v0
	v_cmp_eq_u32_e32 vcc, 0, v0
	s_waitcnt vmcnt(0)
	buffer_inv sc1
	s_and_saveexec_b64 s[10:11], vcc
	s_cbranch_execz .LBB0_343
	s_bcnt1_i32_b64 s8, s[8:9]
	v_mov_b32_e32 v0, s8
	s_nop 0

.LBB0_683:
	s_or_b64 exec, exec, s[4:5]
	v_cvt_f32_u32_e32 v4, v2
	s_waitcnt vmcnt(0)
	v_readfirstlane_b32 s4, v3
	v_sub_u32_e32 v3, 0, v2
	v_rcp_iflag_f32_e32 v4, v4
	v_add_u32_e32 v5, s4, v1
	v_mul_f32_e32 v4, 0x4f7ffffe, v4
	v_cvt_u32_f32_e32 v4, v4
	v_mul_lo_u32 v1, v3, v4
	v_mul_hi_u32 v1, v4, v1
	v_add_u32_e32 v1, v4, v1
	v_mul_hi_u32 v1, v5, v1
	v_mul_lo_u32 v3, v1, v2
	v_sub_u32_e32 v3, v5, v3
	v_add_u32_e32 v4, 1, v1
	v_cmp_ge_u32_e32 vcc, v3, v2
	s_nop 1
	v_cndmask_b32_e32 v1, v1, v4, vcc
	v_sub_u32_e32 v4, v3, v2
	v_cndmask_b32_e32 v3, v3, v4, vcc
	v_add_u32_e32 v4, 1, v1
	v_cmp_ge_u32_e32 vcc, v3, v2
	v_add_u32_e32 v3, 1, v5
	s_nop 0
	v_cndmask_b32_e32 v1, v1, v4, vcc
	v_mul_lo_u32 v4, v2, v1
	v_add_u32_e32 v2, v4, v2
	v_cmp_ne_u32_e32 vcc, v3, v2
	s_and_saveexec_b64 s[4:5], vcc
	s_xor_b64 s[4:5], exec, s[4:5]
	s_cbranch_execz .LBB0_697
	s_waitcnt lgkmcnt(0)
	v_mov_b32_e32 v0, 0
	global_load_dword v2, v0, s[60:61] sc1
	s_waitcnt vmcnt(0)
	v_cmp_eq_u32_e32 vcc, v2, v1
	s_and_saveexec_b64 s[6:7], vcc
	s_cbranch_execz .LBB0_696
	s_mov_b32 s14, 1
	s_mov_b64 s[8:9], 0
	s_branch .LBB0_687

.LBB0_689:
	global_load_dword v2, v0, s[60:61] sc1
	s_add_i32 s14, s14, 1
	s_mov_b64 s[40:41], -1
	s_waitcnt vmcnt(0)
	v_cmp_ne_u32_e32 vcc, v2, v1
	s_orn2_b64 s[12:13], vcc, exec
	s_branch .LBB0_686

.LBB0_714:
	s_or_b64 exec, exec, s[4:5]
	s_mov_b64 s[4:5], exec
	v_mbcnt_lo_u32_b32 v0, s4, 0
	v_mbcnt_hi_u32_b32 v0, s5, v0
	v_cmp_eq_u32_e32 vcc, 0, v0
	s_waitcnt vmcnt(0)
	buffer_inv sc1
	s_and_saveexec_b64 s[6:7], vcc
	s_cbranch_execz .LBB0_716
	s_bcnt1_i32_b64 s4, s[4:5]
	v_mov_b32_e32 v0, 0
	v_mov_b32_e32 v1, s4
	s_nop 0

.LBB0_807:
	s_or_b64 exec, exec, s[2:3]
	v_cvt_f32_u32_e32 v4, v2
	s_waitcnt vmcnt(0)
	v_readfirstlane_b32 s2, v3
	v_sub_u32_e32 v3, 0, v2
	v_rcp_iflag_f32_e32 v4, v4
	v_add_u32_e32 v5, s2, v1
	v_mul_f32_e32 v4, 0x4f7ffffe, v4
	v_cvt_u32_f32_e32 v4, v4
	v_mul_lo_u32 v1, v3, v4
	v_mul_hi_u32 v1, v4, v1
	v_add_u32_e32 v1, v4, v1
	v_mul_hi_u32 v1, v5, v1
	v_mul_lo_u32 v3, v1, v2
	v_sub_u32_e32 v3, v5, v3
	v_add_u32_e32 v4, 1, v1
	v_cmp_ge_u32_e32 vcc, v3, v2
	s_nop 1
	v_cndmask_b32_e32 v1, v1, v4, vcc
	v_sub_u32_e32 v4, v3, v2
	v_cndmask_b32_e32 v3, v3, v4, vcc
	v_add_u32_e32 v4, 1, v1
	v_cmp_ge_u32_e32 vcc, v3, v2
	v_add_u32_e32 v3, 1, v5
	s_nop 0
	v_cndmask_b32_e32 v1, v1, v4, vcc
	v_mul_lo_u32 v4, v2, v1
	v_add_u32_e32 v2, v4, v2
	v_cmp_ne_u32_e32 vcc, v3, v2
	s_and_saveexec_b64 s[2:3], vcc
	s_xor_b64 s[2:3], exec, s[2:3]
	s_cbranch_execz .LBB0_821
	s_waitcnt lgkmcnt(0)
	v_mov_b32_e32 v0, 0
	global_load_dword v2, v0, s[60:61] sc1
	s_waitcnt vmcnt(0)
	v_cmp_eq_u32_e32 vcc, v2, v1
	s_and_saveexec_b64 s[6:7], vcc
	s_cbranch_execz .LBB0_820
	s_mov_b32 s14, 1
	s_mov_b64 s[8:9], 0
	s_branch .LBB0_811

.LBB0_838:
	s_or_b64 exec, exec, s[2:3]
	s_mov_b64 s[2:3], exec
	v_mbcnt_lo_u32_b32 v0, s2, 0
	v_mbcnt_hi_u32_b32 v0, s3, v0
	v_cmp_eq_u32_e32 vcc, 0, v0
	s_waitcnt vmcnt(0)
	buffer_inv sc1
	s_and_saveexec_b64 s[6:7], vcc
	s_cbranch_execz .LBB0_840
	s_bcnt1_i32_b64 s2, s[2:3]
	v_mov_b32_e32 v0, 0
	v_mov_b32_e32 v1, s2
	s_nop 0

.LBB0_883:
	s_or_b64 exec, exec, s[2:3]
	v_cvt_f32_u32_e32 v4, v2
	s_waitcnt vmcnt(0)
	v_readfirstlane_b32 s2, v3
	v_sub_u32_e32 v3, 0, v2
	v_rcp_iflag_f32_e32 v4, v4
	v_add_u32_e32 v5, s2, v1
	v_mul_f32_e32 v4, 0x4f7ffffe, v4
	v_cvt_u32_f32_e32 v4, v4
	v_mul_lo_u32 v1, v3, v4
	v_mul_hi_u32 v1, v4, v1
	v_add_u32_e32 v1, v4, v1
	v_mul_hi_u32 v1, v5, v1
	v_mul_lo_u32 v3, v1, v2
	v_sub_u32_e32 v3, v5, v3
	v_add_u32_e32 v4, 1, v1
	v_cmp_ge_u32_e32 vcc, v3, v2
	s_nop 1
	v_cndmask_b32_e32 v1, v1, v4, vcc
	v_sub_u32_e32 v4, v3, v2
	v_cndmask_b32_e32 v3, v3, v4, vcc
	v_add_u32_e32 v4, 1, v1
	v_cmp_ge_u32_e32 vcc, v3, v2
	v_add_u32_e32 v3, 1, v5
	s_nop 0
	v_cndmask_b32_e32 v1, v1, v4, vcc
	v_mul_lo_u32 v4, v2, v1
	v_add_u32_e32 v2, v4, v2
	v_cmp_ne_u32_e32 vcc, v3, v2
	s_and_saveexec_b64 s[2:3], vcc
	s_xor_b64 s[2:3], exec, s[2:3]
	s_cbranch_execz .LBB0_897
	s_waitcnt lgkmcnt(0)
	v_mov_b32_e32 v0, 0
	global_load_dword v2, v0, s[60:61] sc1
	s_waitcnt vmcnt(0)
	v_cmp_eq_u32_e32 vcc, v2, v1
	s_and_saveexec_b64 s[4:5], vcc
	s_cbranch_execz .LBB0_896
	s_mov_b32 s14, 1
	s_mov_b64 s[6:7], 0
	s_branch .LBB0_887

.LBB0_889:
	global_load_dword v2, v0, s[60:61] sc1
	s_add_i32 s14, s14, 1
	s_mov_b64 s[12:13], -1
	s_waitcnt vmcnt(0)
	v_cmp_ne_u32_e32 vcc, v2, v1
	s_orn2_b64 s[10:11], vcc, exec
	s_branch .LBB0_886

.LBB0_914:
	s_or_b64 exec, exec, s[2:3]
	s_mov_b64 s[2:3], exec
	v_mbcnt_lo_u32_b32 v0, s2, 0
	v_mbcnt_hi_u32_b32 v0, s3, v0
	v_cmp_eq_u32_e32 vcc, 0, v0
	s_waitcnt vmcnt(0)
	buffer_inv sc1
	s_and_saveexec_b64 s[4:5], vcc
	s_cbranch_execz .LBB0_916
	s_bcnt1_i32_b64 s2, s[2:3]
	v_mov_b32_e32 v0, 0
	v_mov_b32_e32 v1, s2
	s_nop 0
